# NSA selected-branch loop: redundant second computation of the selection-bit lane mask removed from the wave-uniform branch test
# baseline (speedup 1.0000x reference)
.LBB0_746:
	s_cmp_lt_i32 s92, 32
	s_cselect_b64 vcc, -1, 0
	s_cmp_lt_u32 s92, 64
	s_cselect_b64 s[72:73], -1, 0
	s_cmpk_lt_u32 s92, 0x60
	s_cselect_b64 s[76:77], -1, 0
	v_cndmask_b32_e64 v101, v147, v146, s[76:77]
	v_cndmask_b32_e64 v101, v101, v145, s[72:73]
	v_cndmask_b32_e32 v101, v101, v144, vcc
	s_and_b32 s76, s92, 31
	v_bfe_u32 v101, v101, s76, 1
	v_cmp_ne_u32_e32 vcc, 0, v101
	s_mov_b64 s[72:73], vcc
	s_cbranch_vccz .LBB0_743
	s_lshl_b32 s76, s91, 14
	s_add_i32 s91, s76, 0
	s_cmp_eq_u32 s92, s33
	s_cbranch_scc0 .Lsel_fast2
	v_add_u32_e32 v0, s91, v184
	ds_read_b128 v[2:5], v0
	ds_read_b128 v[6:9], v0 offset:8192
	v_add_u32_e32 v0, s91, v185
	ds_read_b128 v[10:13], v0
	ds_read_b128 v[208:211], v0 offset:8192
	v_add_u32_e32 v0, s91, v186
	ds_read_b128 v[212:215], v0
	ds_read_b128 v[216:219], v0 offset:8192
	s_waitcnt lgkmcnt(0)
	v_mfma_f32_32x32x16_bf16 v[80:95], v[2:5], v[140:143], 0
	v_mfma_f32_32x32x16_bf16 v[96:111], v[6:9], v[140:143], 0
	v_add_u32_e32 v0, s91, v183
	ds_read_b128 v[2:5], v0
	ds_read_b128 v[6:9], v0 offset:8192
	v_mfma_f32_32x32x16_bf16 v[80:95], v[10:13], v[136:139], v[80:95]
	v_mfma_f32_32x32x16_bf16 v[96:111], v[208:211], v[136:139], v[96:111]
	v_add_u32_e32 v0, s91, v182
	ds_read_b128 v[10:13], v0
	ds_read_b128 v[208:211], v0 offset:8192
	v_mfma_f32_32x32x16_bf16 v[80:95], v[212:215], v[132:135], v[80:95]
	v_mfma_f32_32x32x16_bf16 v[96:111], v[216:219], v[132:135], v[96:111]
	v_add_u32_e32 v0, s91, v181
	ds_read_b128 v[212:215], v0
	ds_read_b128 v[216:219], v0 offset:8192
	s_waitcnt lgkmcnt(0)
	v_mfma_f32_32x32x16_bf16 v[80:95], v[2:5], v[128:131], v[80:95]
	v_mfma_f32_32x32x16_bf16 v[96:111], v[6:9], v[128:131], v[96:111]
	v_add_u32_e32 v0, s91, v180
	ds_read_b128 v[2:5], v0
	ds_read_b128 v[6:9], v0 offset:8192
	v_mfma_f32_32x32x16_bf16 v[80:95], v[10:13], v[124:127], v[80:95]
	v_mfma_f32_32x32x16_bf16 v[96:111], v[208:211], v[124:127], v[96:111]
	v_add_u32_e32 v0, s91, v179
	ds_read_b128 v[10:13], v0
	ds_read_b128 v[208:211], v0 offset:8192
	v_mfma_f32_32x32x16_bf16 v[80:95], v[212:215], v[120:123], v[80:95]
	v_mfma_f32_32x32x16_bf16 v[96:111], v[216:219], v[120:123], v[96:111]
	s_waitcnt lgkmcnt(0)
	v_mfma_f32_32x32x16_bf16 v[80:95], v[2:5], v[116:119], v[80:95]
	v_mfma_f32_32x32x16_bf16 v[96:111], v[6:9], v[116:119], v[96:111]
	v_mfma_f32_32x32x16_bf16 v[80:95], v[10:13], v[112:115], v[80:95]
	v_mfma_f32_32x32x16_bf16 v[96:111], v[208:211], v[112:115], v[96:111]
	s_nop 10
	s_cmp_eq_u32 s92, s33
	s_cbranch_scc0 .Lsel_fast
	v_exp_f32_e32 v6, v80
	v_exp_f32_e32 v0, v96
	v_exp_f32_e32 v9, v81
	v_exp_f32_e32 v3, v97
	v_exp_f32_e32 v8, v82
	v_exp_f32_e32 v2, v98
	v_exp_f32_e32 v11, v83
	v_exp_f32_e32 v5, v99
	v_exp_f32_e32 v10, v84
	v_exp_f32_e32 v4, v100
	v_exp_f32_e32 v13, v85
	v_exp_f32_e32 v7, v101
	v_exp_f32_e32 v96, v86
	v_exp_f32_e32 v82, v102
	v_exp_f32_e32 v97, v87
	v_exp_f32_e32 v83, v103
	v_exp_f32_e32 v88, v88
	v_exp_f32_e32 v14, v104
	v_exp_f32_e32 v89, v89
	v_exp_f32_e32 v15, v105
	v_exp_f32_e32 v90, v90
	v_exp_f32_e32 v80, v106
	v_exp_f32_e32 v91, v91
	v_exp_f32_e32 v81, v107
	v_exp_f32_e32 v92, v92
	v_exp_f32_e32 v84, v108
	v_exp_f32_e32 v93, v93
	v_exp_f32_e32 v85, v109
	v_exp_f32_e32 v94, v94
	v_exp_f32_e32 v86, v110
	v_exp_f32_e32 v95, v95
	v_exp_f32_e32 v87, v111
	s_cmp_eq_u32 s92, s33
	s_mov_b64 s[76:77], -1
	s_cbranch_scc1 .LBB0_749
	s_mov_b64 s[76:77], 0
